# seam and flag poll loops without s_sleep; thread 0's redundant invalidate in the entry grid sync removed
# baseline (speedup 1.0000x reference)
; __global__ void __launch_bounds__(NWAVES * 64, 2) mega_fwd(Args args) {
;     ...
;     if (hi > N_PHASES_K) { asm volatile("s_waitcnt vmcnt(0) lgkmcnt(0)" ::: "memory"); __syncthreads(); grid.sync(); __builtin_amdgcn_fence(__ATOMIC_ACQUIRE, "agent"); asm volatile("s_waitcnt vmcnt(0)" ::: "memory"); }
.LBB0_14:
	global_load_dword v2, v0, s[6:7] offset:32 sc1
	s_waitcnt vmcnt(0)
	v_and_b32_e32 v2, 0xffff0000, v2
	v_cmp_ne_u32_e32 vcc, v2, v1
	s_or_b64 s[0:1], vcc, s[0:1]
	s_andn2_b64 exec, exec, s[0:1]
	s_cbranch_execnz .LBB0_14
.LBB0_15:
.LBB0_16:
	s_or_b64 exec, exec, s[4:5]
	s_barrier
	s_waitcnt vmcnt(0)
	buffer_inv sc1
	s_waitcnt vmcnt(0)

; __device__ __forceinline__ unsigned xb_ld(unsigned* p)              { return __hip_atomic_load(p, __ATOMIC_RELAXED, __HIP_MEMORY_SCOPE_AGENT); }
; __device__ __forceinline__ void xcd_barrier_complete(unsigned* bar, unsigned x, unsigned& nloc, unsigned& nx) {
;     const unsigned G = gridDim.x * gridDim.y * gridDim.z;
;     unsigned sum, cnt, mine, sp = 0u;
;     for (;;) {
;         sum = 0u; cnt = 0u; mine = 0u;
; #pragma unroll
;         for (unsigned j = 0; j < 16; ++j) { const unsigned c = xb_ld(&bar[XB_XCNT(j)]); sum += c; cnt += (c > 0u) ? 1u : 0u; mine = (j == x) ? c : mine; }
;         if (sum == G) break;
;         __builtin_amdgcn_s_sleep(1);
;         if ((++sp & 255u) == 0u) { if (xb_ld(&bar[XB_TMO])) break; if (sp > XB_SPIN_CAP) { atomicAdd(&bar[XB_TMO], 1u); break; } }
;     }
.LBB0_56:
	global_load_dword v15, v16, s[86:87] offset:1024 sc1
	s_waitcnt lgkmcnt(0)
	global_load_dword v0, v16, s[86:87] offset:1280 sc1
	global_load_dword v1, v16, s[86:87] offset:1536 sc1
	global_load_dword v2, v16, s[86:87] offset:1792 sc1
	global_load_dword v3, v16, s[86:87] offset:2048 sc1
	global_load_dword v4, v16, s[86:87] offset:2304 sc1
	global_load_dword v5, v16, s[86:87] offset:2560 sc1
	global_load_dword v6, v16, s[86:87] offset:2816 sc1
	global_load_dword v7, v16, s[86:87] offset:3072 sc1
	global_load_dword v8, v16, s[86:87] offset:3328 sc1
	global_load_dword v9, v16, s[86:87] offset:3584 sc1
	global_load_dword v10, v16, s[86:87] offset:3840 sc1
	global_load_dword v11, v16, s[8:9] sc1
	global_load_dword v12, v16, s[10:11] sc1
	global_load_dword v13, v16, s[12:13] sc1
	global_load_dword v14, v16, s[14:15] sc1
	s_mov_b64 s[0:1], -1
	s_mov_b64 s[16:17], -1
	s_waitcnt vmcnt(14)
	v_add_u32_e32 v17, v0, v15
	s_waitcnt vmcnt(13)
	v_add_u32_e32 v17, v17, v1
	s_waitcnt vmcnt(12)
	v_add_u32_e32 v17, v17, v2
	s_waitcnt vmcnt(11)
	v_add_u32_e32 v17, v17, v3
	s_waitcnt vmcnt(10)
	v_add_u32_e32 v17, v17, v4
	s_waitcnt vmcnt(9)
	v_add_u32_e32 v17, v17, v5
	s_waitcnt vmcnt(8)
	v_add_u32_e32 v17, v17, v6
	s_waitcnt vmcnt(7)
	v_add_u32_e32 v17, v17, v7
	s_waitcnt vmcnt(6)
	v_add_u32_e32 v17, v17, v8
	s_waitcnt vmcnt(5)
	v_add_u32_e32 v17, v17, v9
	s_waitcnt vmcnt(4)
	v_add_u32_e32 v17, v17, v10
	s_waitcnt vmcnt(3)
	v_add_u32_e32 v17, v17, v11
	s_waitcnt vmcnt(2)
	v_add_u32_e32 v17, v17, v12
	s_waitcnt vmcnt(1)
	v_add_u32_e32 v17, v17, v13
	s_waitcnt vmcnt(0)
	v_add_u32_e32 v17, v17, v14
	v_cmp_eq_u32_e32 vcc, s3, v17
	s_cbranch_vccnz .LBB0_55
	s_and_b32 s0, s20, 0xff
	s_cmp_eq_u32 s0, 0
	s_mov_b64 s[0:1], -1
	s_mov_b64 s[18:19], -1
	s_cbranch_scc1 .LBB0_60
	s_and_b64 vcc, exec, s[18:19]
	s_cbranch_vccz .LBB0_55

; __device__ __forceinline__ unsigned xb_ld(unsigned* p)              { return __hip_atomic_load(p, __ATOMIC_RELAXED, __HIP_MEMORY_SCOPE_AGENT); }
; __device__ __forceinline__ unsigned xb_add(unsigned* p, unsigned v) { return __hip_atomic_fetch_add(p, v, __ATOMIC_RELAXED, __HIP_MEMORY_SCOPE_AGENT); }
; #define XB_SPIN(cond, bar) do { unsigned _sp = 0; while (cond) { __builtin_amdgcn_s_sleep(1); \
;     if ((++_sp & 255u) == 0u) { if (xb_ld(&(bar)[XB_TMO])) break; if (_sp > XB_SPIN_CAP) { atomicAdd(&(bar)[XB_TMO], 1u); break; } } } } while (0)
; __device__ __forceinline__ void xcd_barrier(const XcdBarrier& b) {
;     ...
;             const unsigned og = xb_add(&bar[XB_TOP], 1u);
;             const unsigned tg = og / nx;
;             if (og + 1u == (tg + 1u) * nx) xb_add(&bar[XB_TOPGEN], 1u);
;             else XB_SPIN(xb_ld(&bar[XB_TOPGEN]) == tg, bar);
;             __builtin_amdgcn_fence(__ATOMIC_ACQUIRE, "agent");
;             xb_add(&bar[XB_XGEN(b.x)], 1u);
;             asm volatile("s_waitcnt vmcnt(0)" ::: "memory");
;         } else {
;             XB_SPIN(xb_ld(&bar[XB_XGEN(b.x)]) == gen, bar);
.LBB0_74:
	s_and_b32 s20, s3, 0xff
	s_mov_b64 s[0:1], -1
	s_cmp_lg_u32 s20, 0
	s_mov_b64 s[22:23], -1
	s_cbranch_scc0 .LBB0_77
	s_and_b64 vcc, exec, s[22:23]
	s_cbranch_vccz .LBB0_73

; __device__ __forceinline__ unsigned xb_ld(unsigned* p)              { return __hip_atomic_load(p, __ATOMIC_RELAXED, __HIP_MEMORY_SCOPE_AGENT); }
; __device__ __forceinline__ unsigned xb_add(unsigned* p, unsigned v) { return __hip_atomic_fetch_add(p, v, __ATOMIC_RELAXED, __HIP_MEMORY_SCOPE_AGENT); }
; #define XB_SPIN(cond, bar) do { unsigned _sp = 0; while (cond) { __builtin_amdgcn_s_sleep(1); \
;     if ((++_sp & 255u) == 0u) { if (xb_ld(&(bar)[XB_TMO])) break; if (_sp > XB_SPIN_CAP) { atomicAdd(&(bar)[XB_TMO], 1u); break; } } } } while (0)
; __device__ __forceinline__ void xcd_barrier(const XcdBarrier& b) {
;     ...
;             const unsigned og = xb_add(&bar[XB_TOP], 1u);
;             const unsigned tg = og / nx;
;             if (og + 1u == (tg + 1u) * nx) xb_add(&bar[XB_TOPGEN], 1u);
;             else XB_SPIN(xb_ld(&bar[XB_TOPGEN]) == tg, bar);
;             __builtin_amdgcn_fence(__ATOMIC_ACQUIRE, "agent");
.LBB0_91:
	s_and_b32 s0, s3, 0xff
	s_cmp_lg_u32 s0, 0
	s_mov_b64 s[22:23], -1
	s_cbranch_scc0 .LBB0_94
	s_mov_b64 s[24:25], -1
	s_and_b64 vcc, exec, s[22:23]
	s_cbranch_vccz .LBB0_90

; __device__ __forceinline__ unsigned xb_ld(unsigned* p)              { return __hip_atomic_load(p, __ATOMIC_RELAXED, __HIP_MEMORY_SCOPE_AGENT); }
; __device__ __forceinline__ void xcd_barrier_complete(unsigned* bar, unsigned x, unsigned& nloc, unsigned& nx) {
;     const unsigned G = gridDim.x * gridDim.y * gridDim.z;
;     unsigned sum, cnt, mine, sp = 0u;
;     for (;;) {
;         sum = 0u; cnt = 0u; mine = 0u;
; #pragma unroll
;         for (unsigned j = 0; j < 16; ++j) { const unsigned c = xb_ld(&bar[XB_XCNT(j)]); sum += c; cnt += (c > 0u) ? 1u : 0u; mine = (j == x) ? c : mine; }
;         if (sum == G) break;
;         __builtin_amdgcn_s_sleep(1);
;         if ((++sp & 255u) == 0u) { if (xb_ld(&bar[XB_TMO])) break; if (sp > XB_SPIN_CAP) { atomicAdd(&bar[XB_TMO], 1u); break; } }
;     }
.LBB0_1797:
	global_load_dword v15, v16, s[86:87] offset:1024 sc1
	s_waitcnt lgkmcnt(0)
	global_load_dword v0, v16, s[86:87] offset:1280 sc1
	global_load_dword v1, v16, s[86:87] offset:1536 sc1
	global_load_dword v2, v16, s[86:87] offset:1792 sc1
	global_load_dword v3, v16, s[86:87] offset:2048 sc1
	global_load_dword v4, v16, s[86:87] offset:2304 sc1
	global_load_dword v5, v16, s[86:87] offset:2560 sc1
	global_load_dword v6, v16, s[86:87] offset:2816 sc1
	global_load_dword v7, v16, s[86:87] offset:3072 sc1
	global_load_dword v8, v16, s[86:87] offset:3328 sc1
	global_load_dword v9, v16, s[86:87] offset:3584 sc1
	global_load_dword v10, v16, s[86:87] offset:3840 sc1
	global_load_dword v11, v16, s[6:7] sc1
	global_load_dword v12, v16, s[8:9] sc1
	global_load_dword v13, v16, s[10:11] sc1
	global_load_dword v14, v16, s[12:13] sc1
	s_mov_b64 s[0:1], -1
	s_mov_b64 s[14:15], -1
	s_waitcnt vmcnt(14)
	v_add_u32_e32 v17, v0, v15
	s_waitcnt vmcnt(13)
	v_add_u32_e32 v17, v17, v1
	s_waitcnt vmcnt(12)
	v_add_u32_e32 v17, v17, v2
	s_waitcnt vmcnt(11)
	v_add_u32_e32 v17, v17, v3
	s_waitcnt vmcnt(10)
	v_add_u32_e32 v17, v17, v4
	s_waitcnt vmcnt(9)
	v_add_u32_e32 v17, v17, v5
	s_waitcnt vmcnt(8)
	v_add_u32_e32 v17, v17, v6
	s_waitcnt vmcnt(7)
	v_add_u32_e32 v17, v17, v7
	s_waitcnt vmcnt(6)
	v_add_u32_e32 v17, v17, v8
	s_waitcnt vmcnt(5)
	v_add_u32_e32 v17, v17, v9
	s_waitcnt vmcnt(4)
	v_add_u32_e32 v17, v17, v10
	s_waitcnt vmcnt(3)
	v_add_u32_e32 v17, v17, v11
	s_waitcnt vmcnt(2)
	v_add_u32_e32 v17, v17, v12
	s_waitcnt vmcnt(1)
	v_add_u32_e32 v17, v17, v13
	s_waitcnt vmcnt(0)
	v_add_u32_e32 v17, v17, v14
	v_cmp_eq_u32_e32 vcc, s3, v17
	s_cbranch_vccnz .LBB0_1796
	s_and_b32 s0, s18, 0xff
	s_cmp_eq_u32 s0, 0
	s_mov_b64 s[0:1], -1
	s_mov_b64 s[16:17], -1
	s_cbranch_scc1 .LBB0_1801
	s_and_b64 vcc, exec, s[16:17]
	s_cbranch_vccz .LBB0_1796

; __device__ __forceinline__ unsigned xb_ld(unsigned* p)              { return __hip_atomic_load(p, __ATOMIC_RELAXED, __HIP_MEMORY_SCOPE_AGENT); }
; __device__ __forceinline__ unsigned xb_add(unsigned* p, unsigned v) { return __hip_atomic_fetch_add(p, v, __ATOMIC_RELAXED, __HIP_MEMORY_SCOPE_AGENT); }
; #define XB_SPIN(cond, bar) do { unsigned _sp = 0; while (cond) { __builtin_amdgcn_s_sleep(1); \
;     if ((++_sp & 255u) == 0u) { if (xb_ld(&(bar)[XB_TMO])) break; if (_sp > XB_SPIN_CAP) { atomicAdd(&(bar)[XB_TMO], 1u); break; } } } } while (0)
; __device__ __forceinline__ void xcd_barrier(const XcdBarrier& b) {
;     ...
;             const unsigned og = xb_add(&bar[XB_TOP], 1u);
;             const unsigned tg = og / nx;
;             if (og + 1u == (tg + 1u) * nx) xb_add(&bar[XB_TOPGEN], 1u);
;             else XB_SPIN(xb_ld(&bar[XB_TOPGEN]) == tg, bar);
;             __builtin_amdgcn_fence(__ATOMIC_ACQUIRE, "agent");
;             xb_add(&bar[XB_XGEN(b.x)], 1u);
;             asm volatile("s_waitcnt vmcnt(0)" ::: "memory");
;         } else {
;             XB_SPIN(xb_ld(&bar[XB_XGEN(b.x)]) == gen, bar);
.LBB0_1815:
	s_and_b32 s18, s3, 0xff
	s_mov_b64 s[0:1], -1
	s_cmp_lg_u32 s18, 0
	s_mov_b64 s[20:21], -1
	s_cbranch_scc0 .LBB0_1818
	s_and_b64 vcc, exec, s[20:21]
	s_cbranch_vccz .LBB0_1814

; __device__ __forceinline__ unsigned xb_ld(unsigned* p)              { return __hip_atomic_load(p, __ATOMIC_RELAXED, __HIP_MEMORY_SCOPE_AGENT); }
; __device__ __forceinline__ unsigned xb_add(unsigned* p, unsigned v) { return __hip_atomic_fetch_add(p, v, __ATOMIC_RELAXED, __HIP_MEMORY_SCOPE_AGENT); }
; #define XB_SPIN(cond, bar) do { unsigned _sp = 0; while (cond) { __builtin_amdgcn_s_sleep(1); \
;     if ((++_sp & 255u) == 0u) { if (xb_ld(&(bar)[XB_TMO])) break; if (_sp > XB_SPIN_CAP) { atomicAdd(&(bar)[XB_TMO], 1u); break; } } } } while (0)
; __device__ __forceinline__ void xcd_barrier(const XcdBarrier& b) {
;     ...
;             const unsigned og = xb_add(&bar[XB_TOP], 1u);
;             const unsigned tg = og / nx;
;             if (og + 1u == (tg + 1u) * nx) xb_add(&bar[XB_TOPGEN], 1u);
;             else XB_SPIN(xb_ld(&bar[XB_TOPGEN]) == tg, bar);
;             __builtin_amdgcn_fence(__ATOMIC_ACQUIRE, "agent");
.LBB0_1832:
	s_and_b32 s0, s3, 0xff
	s_cmp_lg_u32 s0, 0
	s_mov_b64 s[20:21], -1
	s_cbranch_scc0 .LBB0_1835
	s_mov_b64 s[22:23], -1
	s_and_b64 vcc, exec, s[20:21]
	s_cbranch_vccz .LBB0_1831

; __device__ __forceinline__ unsigned xb_ld(unsigned* p)              { return __hip_atomic_load(p, __ATOMIC_RELAXED, __HIP_MEMORY_SCOPE_AGENT); }
; __device__ __forceinline__ void xcd_barrier_complete(unsigned* bar, unsigned x, unsigned& nloc, unsigned& nx) {
;     const unsigned G = gridDim.x * gridDim.y * gridDim.z;
;     unsigned sum, cnt, mine, sp = 0u;
;     for (;;) {
;         sum = 0u; cnt = 0u; mine = 0u;
; #pragma unroll
;         for (unsigned j = 0; j < 16; ++j) { const unsigned c = xb_ld(&bar[XB_XCNT(j)]); sum += c; cnt += (c > 0u) ? 1u : 0u; mine = (j == x) ? c : mine; }
;         if (sum == G) break;
;         __builtin_amdgcn_s_sleep(1);
;         if ((++sp & 255u) == 0u) { if (xb_ld(&bar[XB_TMO])) break; if (sp > XB_SPIN_CAP) { atomicAdd(&bar[XB_TMO], 1u); break; } }
;     }
.LBB0_1922:
	global_load_dword v15, v16, s[86:87] offset:1024 sc1
	s_waitcnt lgkmcnt(0)
	global_load_dword v0, v16, s[86:87] offset:1280 sc1
	global_load_dword v1, v16, s[86:87] offset:1536 sc1
	global_load_dword v2, v16, s[86:87] offset:1792 sc1
	global_load_dword v3, v16, s[86:87] offset:2048 sc1
	global_load_dword v4, v16, s[86:87] offset:2304 sc1
	global_load_dword v5, v16, s[86:87] offset:2560 sc1
	global_load_dword v6, v16, s[86:87] offset:2816 sc1
	global_load_dword v7, v16, s[86:87] offset:3072 sc1
	global_load_dword v8, v16, s[86:87] offset:3328 sc1
	global_load_dword v9, v16, s[86:87] offset:3584 sc1
	global_load_dword v10, v16, s[86:87] offset:3840 sc1
	global_load_dword v11, v16, s[6:7] sc1
	global_load_dword v12, v16, s[8:9] sc1
	global_load_dword v13, v16, s[10:11] sc1
	global_load_dword v14, v16, s[12:13] sc1
	s_mov_b64 s[0:1], -1
	s_mov_b64 s[14:15], -1
	s_waitcnt vmcnt(14)
	v_add_u32_e32 v17, v0, v15
	s_waitcnt vmcnt(13)
	v_add_u32_e32 v17, v17, v1
	s_waitcnt vmcnt(12)
	v_add_u32_e32 v17, v17, v2
	s_waitcnt vmcnt(11)
	v_add_u32_e32 v17, v17, v3
	s_waitcnt vmcnt(10)
	v_add_u32_e32 v17, v17, v4
	s_waitcnt vmcnt(9)
	v_add_u32_e32 v17, v17, v5
	s_waitcnt vmcnt(8)
	v_add_u32_e32 v17, v17, v6
	s_waitcnt vmcnt(7)
	v_add_u32_e32 v17, v17, v7
	s_waitcnt vmcnt(6)
	v_add_u32_e32 v17, v17, v8
	s_waitcnt vmcnt(5)
	v_add_u32_e32 v17, v17, v9
	s_waitcnt vmcnt(4)
	v_add_u32_e32 v17, v17, v10
	s_waitcnt vmcnt(3)
	v_add_u32_e32 v17, v17, v11
	s_waitcnt vmcnt(2)
	v_add_u32_e32 v17, v17, v12
	s_waitcnt vmcnt(1)
	v_add_u32_e32 v17, v17, v13
	s_waitcnt vmcnt(0)
	v_add_u32_e32 v17, v17, v14
	v_cmp_eq_u32_e32 vcc, s18, v17
	s_cbranch_vccnz .LBB0_1921
	s_and_b32 s0, s19, 0xff
	s_cmp_eq_u32 s0, 0
	s_mov_b64 s[0:1], -1
	s_mov_b64 s[16:17], -1
	s_cbranch_scc1 .LBB0_1926
	s_and_b64 vcc, exec, s[16:17]
	s_cbranch_vccz .LBB0_1921

; __device__ __forceinline__ unsigned xb_ld(unsigned* p)              { return __hip_atomic_load(p, __ATOMIC_RELAXED, __HIP_MEMORY_SCOPE_AGENT); }
; __device__ __forceinline__ unsigned xb_add(unsigned* p, unsigned v) { return __hip_atomic_fetch_add(p, v, __ATOMIC_RELAXED, __HIP_MEMORY_SCOPE_AGENT); }
; #define XB_SPIN(cond, bar) do { unsigned _sp = 0; while (cond) { __builtin_amdgcn_s_sleep(1); \
;     if ((++_sp & 255u) == 0u) { if (xb_ld(&(bar)[XB_TMO])) break; if (_sp > XB_SPIN_CAP) { atomicAdd(&(bar)[XB_TMO], 1u); break; } } } } while (0)
; __device__ __forceinline__ void xcd_barrier(const XcdBarrier& b) {
;     ...
;             const unsigned og = xb_add(&bar[XB_TOP], 1u);
;             const unsigned tg = og / nx;
;             if (og + 1u == (tg + 1u) * nx) xb_add(&bar[XB_TOPGEN], 1u);
;             else XB_SPIN(xb_ld(&bar[XB_TOPGEN]) == tg, bar);
;             __builtin_amdgcn_fence(__ATOMIC_ACQUIRE, "agent");
;             xb_add(&bar[XB_XGEN(b.x)], 1u);
;             asm volatile("s_waitcnt vmcnt(0)" ::: "memory");
;         } else {
;             XB_SPIN(xb_ld(&bar[XB_XGEN(b.x)]) == gen, bar);
.LBB0_1940:
	s_and_b32 s18, s22, 0xff
	s_mov_b64 s[0:1], -1
	s_cmp_lg_u32 s18, 0
	s_mov_b64 s[20:21], -1
	s_cbranch_scc0 .LBB0_1943
	s_and_b64 vcc, exec, s[20:21]
	s_cbranch_vccz .LBB0_1939

; __device__ __forceinline__ unsigned xb_ld(unsigned* p)              { return __hip_atomic_load(p, __ATOMIC_RELAXED, __HIP_MEMORY_SCOPE_AGENT); }
; __device__ __forceinline__ unsigned xb_add(unsigned* p, unsigned v) { return __hip_atomic_fetch_add(p, v, __ATOMIC_RELAXED, __HIP_MEMORY_SCOPE_AGENT); }
; #define XB_SPIN(cond, bar) do { unsigned _sp = 0; while (cond) { __builtin_amdgcn_s_sleep(1); \
;     if ((++_sp & 255u) == 0u) { if (xb_ld(&(bar)[XB_TMO])) break; if (_sp > XB_SPIN_CAP) { atomicAdd(&(bar)[XB_TMO], 1u); break; } } } } while (0)
; __device__ __forceinline__ void xcd_barrier(const XcdBarrier& b) {
;     ...
;             const unsigned og = xb_add(&bar[XB_TOP], 1u);
;             const unsigned tg = og / nx;
;             if (og + 1u == (tg + 1u) * nx) xb_add(&bar[XB_TOPGEN], 1u);
;             else XB_SPIN(xb_ld(&bar[XB_TOPGEN]) == tg, bar);
;             __builtin_amdgcn_fence(__ATOMIC_ACQUIRE, "agent");
.LBB0_1957:
	s_and_b32 s0, s24, 0xff
	s_cmp_lg_u32 s0, 0
	s_mov_b64 s[20:21], -1
	s_cbranch_scc0 .LBB0_1960
	s_mov_b64 s[22:23], -1
	s_and_b64 vcc, exec, s[20:21]
	s_cbranch_vccz .LBB0_1956
